# unit-start vmcnt(0) in the accumulator zeroing blocks of GEMM2 pieces, GEMM3 and GEMM4 replaced by s_nop: the next unit K-loop starts while the epilogue stores still drain
# speedup vs baseline: 1.0024x; 1.0024x over previous
; template <class Epi, class Sched, bool ALIGN_EPI = false, bool SP2 = false, bool A_TILED = false, bool B_TILED = false>
; __device__ __forceinline__ void gemm_phase(PG8_LAS unsigned char* lds, const Gemm g, const Sched& S, const Epi& E) {
;     ...
;         if (!chain) {
; #pragma unroll
;         for (int a = 0; a < 2; ++a)
; #pragma unroll
;             for (int b = 0; b < 2; ++b)
; #pragma unroll
;                 for (int m = 0; m < 4; ++m)
; #pragma unroll
;                     for (int n = 0; n < 2; ++n) acc[a][b][m][n] = (f32x4){0.f, 0.f, 0.f, 0.f};
;         }
;         cur = nxt; cA = nA; cB = nB; ++ui; nt = cur.nt;
.LBB0_552:
	s_ashr_i32 s25, s24, 31
	s_lshl_b64 s[30:31], s[24:25], 21
	s_add_u32 s5, s33, s30
	s_addc_u32 s7, s46, s31
	s_ashr_i32 s27, s26, 31
	s_lshl_b64 s[34:35], s[26:27], 7
	s_add_u32 s30, s5, s34
	s_addc_u32 s31, s7, s35
	s_and_b64 s[40:41], s[28:29], exec
	s_cselect_b32 s5, s31, s37
	s_cselect_b32 s7, s30, s36
	s_ashr_i32 s23, s22, 31
	s_lshl_b64 s[40:41], s[22:23], 21
	s_add_u32 s23, s47, s40
	s_addc_u32 s25, s52, s41
	s_add_u32 s34, s23, s34
	s_addc_u32 s35, s25, s35
	s_and_b64 s[40:41], s[28:29], exec
	s_cselect_b32 s23, s35, s39
	s_cselect_b32 s25, s34, s38
	s_add_u32 s36, s36, 0x100080
	s_addc_u32 s37, s37, 0
	s_add_u32 s27, s38, 0x100
	v_mov_b32_e32 v2, 0
	s_addc_u32 s58, s39, 0
	s_mov_b32 s59, -2
	v_mov_b32_e32 v3, v2
	v_mov_b32_e32 v4, v2
	v_mov_b32_e32 v5, v2
	v_mov_b32_e32 v6, v2
	v_mov_b32_e32 v7, v2
	v_mov_b32_e32 v8, v2
	v_mov_b32_e32 v9, v2
	v_mov_b32_e32 v18, v2
	v_mov_b32_e32 v19, v2
	v_mov_b32_e32 v20, v2
	v_mov_b32_e32 v21, v2
	v_mov_b32_e32 v22, v2
	v_mov_b32_e32 v23, v2
	v_mov_b32_e32 v24, v2
	v_mov_b32_e32 v25, v2
	v_mov_b32_e32 v34, v2
	v_mov_b32_e32 v35, v2
	v_mov_b32_e32 v36, v2
	v_mov_b32_e32 v37, v2
	v_mov_b32_e32 v38, v2
	v_mov_b32_e32 v39, v2
	v_mov_b32_e32 v40, v2
	v_mov_b32_e32 v41, v2
	s_nop 0
	v_mov_b32_e32 v50, v2
	v_mov_b32_e32 v51, v2
	v_mov_b32_e32 v52, v2
	v_mov_b32_e32 v53, v2
	v_mov_b32_e32 v54, v2
	v_mov_b32_e32 v55, v2
	v_mov_b32_e32 v56, v2
	v_mov_b32_e32 v57, v2
	v_mov_b32_e32 v10, v2
	v_mov_b32_e32 v11, v2
	v_mov_b32_e32 v12, v2
	v_mov_b32_e32 v13, v2
	v_mov_b32_e32 v14, v2
	v_mov_b32_e32 v15, v2
	v_mov_b32_e32 v16, v2
	v_mov_b32_e32 v17, v2
	v_mov_b32_e32 v26, v2
	v_mov_b32_e32 v27, v2
	v_mov_b32_e32 v28, v2
	v_mov_b32_e32 v29, v2
	v_mov_b32_e32 v30, v2
	v_mov_b32_e32 v31, v2
	v_mov_b32_e32 v32, v2
	v_mov_b32_e32 v33, v2
	v_mov_b32_e32 v42, v2
	v_mov_b32_e32 v43, v2
	v_mov_b32_e32 v44, v2
	v_mov_b32_e32 v45, v2
	v_mov_b32_e32 v46, v2
	v_mov_b32_e32 v47, v2
	v_mov_b32_e32 v48, v2
	v_mov_b32_e32 v49, v2
	v_mov_b32_e32 v58, v2
	v_mov_b32_e32 v59, v2
	v_mov_b32_e32 v60, v2
	v_mov_b32_e32 v61, v2
	v_mov_b32_e32 v62, v2
	v_mov_b32_e32 v63, v2
	v_mov_b32_e32 v64, v2
	v_mov_b32_e32 v65, v2
	v_mov_b32_e32 v66, v2
	v_mov_b32_e32 v67, v2
	v_mov_b32_e32 v68, v2
	v_mov_b32_e32 v69, v2
	v_mov_b32_e32 v70, v2
	v_mov_b32_e32 v71, v2
	v_mov_b32_e32 v72, v2
	v_mov_b32_e32 v73, v2
	v_mov_b32_e32 v82, v2
	v_mov_b32_e32 v83, v2
	v_mov_b32_e32 v84, v2
	v_mov_b32_e32 v85, v2
	v_mov_b32_e32 v86, v2
	v_mov_b32_e32 v87, v2
	v_mov_b32_e32 v88, v2
	v_mov_b32_e32 v89, v2
	v_mov_b32_e32 v98, v2
	v_mov_b32_e32 v99, v2
	v_mov_b32_e32 v100, v2
	v_mov_b32_e32 v101, v2
	v_mov_b32_e32 v102, v2
	v_mov_b32_e32 v103, v2
	v_mov_b32_e32 v104, v2
	v_mov_b32_e32 v105, v2
	v_mov_b32_e32 v114, v2
	v_mov_b32_e32 v115, v2
	v_mov_b32_e32 v116, v2
	v_mov_b32_e32 v117, v2
	v_mov_b32_e32 v118, v2
	v_mov_b32_e32 v119, v2
	v_mov_b32_e32 v120, v2
	v_mov_b32_e32 v121, v2
	v_mov_b32_e32 v74, v2
	v_mov_b32_e32 v75, v2
	v_mov_b32_e32 v76, v2
	v_mov_b32_e32 v77, v2
	v_mov_b32_e32 v78, v2
	v_mov_b32_e32 v79, v2
	v_mov_b32_e32 v80, v2
	v_mov_b32_e32 v81, v2
	v_mov_b32_e32 v90, v2
	v_mov_b32_e32 v91, v2
	v_mov_b32_e32 v92, v2
	v_mov_b32_e32 v93, v2
	v_mov_b32_e32 v94, v2
	v_mov_b32_e32 v95, v2
	v_mov_b32_e32 v96, v2
	v_mov_b32_e32 v97, v2
	v_mov_b32_e32 v106, v2
	v_mov_b32_e32 v107, v2
	v_mov_b32_e32 v108, v2
	v_mov_b32_e32 v109, v2
	v_mov_b32_e32 v110, v2
	v_mov_b32_e32 v111, v2
	v_mov_b32_e32 v112, v2
	v_mov_b32_e32 v113, v2
	v_mov_b32_e32 v122, v2
	v_mov_b32_e32 v123, v2
	v_mov_b32_e32 v124, v2
	v_mov_b32_e32 v125, v2
	v_mov_b32_e32 v126, v2
	v_mov_b32_e32 v127, v2
	v_mov_b32_e32 v128, v2
	v_mov_b32_e32 v129, v2

; #define PG8_LAS __attribute__((address_space(3)))
; template <class Epi, class Sched, bool ALIGN_EPI = false, bool SP2 = false, bool A_TILED = false, bool B_TILED = false>
; __device__ __forceinline__ void gemm_phase(PG8_LAS unsigned char* lds, const Gemm g, const Sched& S, const Epi& E) {
;     ...
;         if (!chain) {
; #pragma unroll
;         for (int a = 0; a < 2; ++a)
; #pragma unroll
;             for (int b = 0; b < 2; ++b)
; #pragma unroll
;                 for (int m = 0; m < 4; ++m)
; #pragma unroll
;                     for (int n = 0; n < 2; ++n) acc[a][b][m][n] = (f32x4){0.f, 0.f, 0.f, 0.f};
;         }
;         cur = nxt; cA = nA; cB = nB; ++ui; nt = cur.nt;
;     __device__ __forceinline__ void operator()(const f32x4 (&acc)[2][2][4][2], const Unit& u, int wr, int wc, int fr, int fq) const {
;     ...
;         const float* sq = ssq + u.pm * BM + wr * 64 + fr;
;     ...
;         PG8_LAS float* const T = E - 2048;
;         { const int tid_ = threadIdx.x; if (tid_ < 256) E[1024 + tid_] = 1.0f / sqrtf(ssq[u.pm * BM + tid_] * (1.0f / DM) + EPS);
.LBB0_725:
	s_mov_b32 s64, s16
	s_ashr_i32 s65, s16, 31
	s_lshl_b64 s[12:13], s[64:65], 21
	s_add_u32 s70, s88, s12
	s_addc_u32 s71, s89, s13
	s_and_b64 s[12:13], s[68:69], exec
	s_mov_b32 s66, s17
	s_cselect_b32 s7, s71, s9
	s_cselect_b32 s14, s70, s8
	s_ashr_i32 s67, s17, 31
	s_lshl_b64 s[12:13], s[66:67], 21
	s_add_u32 s72, s90, s12
	s_addc_u32 s73, s91, s13
	s_and_b64 s[12:13], s[68:69], exec
	s_cselect_b32 s15, s73, s11
	s_cselect_b32 s16, s72, s10
	s_add_u32 s8, s8, 0x100080
	s_addc_u32 s9, s9, 0
	s_add_u32 s17, s10, 0x100
	v_mov_b32_e32 v6, 0
	s_addc_u32 s18, s11, 0
	s_mov_b32 s19, -2
	v_mov_b32_e32 v7, v6
	v_mov_b32_e32 v8, v6
	v_mov_b32_e32 v9, v6
	v_mov_b32_e32 v70, v6
	v_mov_b32_e32 v71, v6
	v_mov_b32_e32 v72, v6
	v_mov_b32_e32 v73, v6
	v_mov_b32_e32 v18, v6
	v_mov_b32_e32 v19, v6
	v_mov_b32_e32 v20, v6
	v_mov_b32_e32 v21, v6
	v_mov_b32_e32 v82, v6
	v_mov_b32_e32 v83, v6
	v_mov_b32_e32 v84, v6
	v_mov_b32_e32 v85, v6
	v_mov_b32_e32 v26, v6
	v_mov_b32_e32 v27, v6
	v_mov_b32_e32 v28, v6
	v_mov_b32_e32 v29, v6
	v_mov_b32_e32 v90, v6
	v_mov_b32_e32 v91, v6
	v_mov_b32_e32 v92, v6
	v_mov_b32_e32 v93, v6
	v_mov_b32_e32 v34, v6
	v_mov_b32_e32 v35, v6
	v_mov_b32_e32 v36, v6
	v_mov_b32_e32 v37, v6
	v_mov_b32_e32 v98, v6
	v_mov_b32_e32 v99, v6
	v_mov_b32_e32 v100, v6
	v_mov_b32_e32 v101, v6
	v_mov_b32_e32 v14, v6
	v_mov_b32_e32 v15, v6
	v_mov_b32_e32 v16, v6
	v_mov_b32_e32 v17, v6
	v_mov_b32_e32 v78, v6
	v_mov_b32_e32 v79, v6
	v_mov_b32_e32 v80, v6
	v_mov_b32_e32 v81, v6
	v_mov_b32_e32 v10, v6
	v_mov_b32_e32 v11, v6
	v_mov_b32_e32 v12, v6
	v_mov_b32_e32 v13, v6
	v_mov_b32_e32 v74, v6
	v_mov_b32_e32 v75, v6
	v_mov_b32_e32 v76, v6
	v_mov_b32_e32 v77, v6
	v_mov_b32_e32 v22, v6
	v_mov_b32_e32 v23, v6
	v_mov_b32_e32 v24, v6
	v_mov_b32_e32 v25, v6
	v_mov_b32_e32 v86, v6
	v_mov_b32_e32 v87, v6
	v_mov_b32_e32 v88, v6
	v_mov_b32_e32 v89, v6
	v_mov_b32_e32 v30, v6
	v_mov_b32_e32 v31, v6
	v_mov_b32_e32 v32, v6
	v_mov_b32_e32 v33, v6
	v_mov_b32_e32 v94, v6
	v_mov_b32_e32 v95, v6
	v_mov_b32_e32 v96, v6
	v_mov_b32_e32 v97, v6
	v_mov_b32_e32 v38, v6
	v_mov_b32_e32 v39, v6
	v_mov_b32_e32 v40, v6
	v_mov_b32_e32 v41, v6
	v_mov_b32_e32 v102, v6
	v_mov_b32_e32 v103, v6
	v_mov_b32_e32 v104, v6
	v_mov_b32_e32 v105, v6
	s_nop 0
	v_mov_b32_e32 v50, v6
	v_mov_b32_e32 v51, v6
	v_mov_b32_e32 v52, v6
	v_mov_b32_e32 v53, v6
	v_mov_b32_e32 v114, v6
	v_mov_b32_e32 v115, v6
	v_mov_b32_e32 v116, v6
	v_mov_b32_e32 v117, v6
	v_mov_b32_e32 v58, v6
	v_mov_b32_e32 v59, v6
	v_mov_b32_e32 v60, v6
	v_mov_b32_e32 v61, v6
	v_mov_b32_e32 v142, v6
	v_mov_b32_e32 v143, v6
	v_mov_b32_e32 v144, v6
	v_mov_b32_e32 v145, v6
	v_mov_b32_e32 v66, v6
	v_mov_b32_e32 v67, v6
	v_mov_b32_e32 v68, v6
	v_mov_b32_e32 v69, v6
	v_mov_b32_e32 v118, v6
	v_mov_b32_e32 v119, v6
	v_mov_b32_e32 v120, v6
	v_mov_b32_e32 v121, v6
	v_mov_b32_e32 v46, v6
	v_mov_b32_e32 v47, v6
	v_mov_b32_e32 v48, v6
	v_mov_b32_e32 v49, v6
	v_mov_b32_e32 v110, v6
	v_mov_b32_e32 v111, v6
	v_mov_b32_e32 v112, v6
	v_mov_b32_e32 v113, v6
	v_mov_b32_e32 v42, v6
	v_mov_b32_e32 v43, v6
	v_mov_b32_e32 v44, v6
	v_mov_b32_e32 v45, v6
	v_mov_b32_e32 v106, v6
	v_mov_b32_e32 v107, v6
	v_mov_b32_e32 v108, v6
	v_mov_b32_e32 v109, v6
	v_mov_b32_e32 v54, v6
	v_mov_b32_e32 v55, v6
	v_mov_b32_e32 v56, v6
	v_mov_b32_e32 v57, v6
	v_mov_b32_e32 v122, v6
	v_mov_b32_e32 v123, v6
	v_mov_b32_e32 v124, v6
	v_mov_b32_e32 v125, v6
	v_mov_b32_e32 v62, v6
	v_mov_b32_e32 v63, v6
	v_mov_b32_e32 v64, v6
	v_mov_b32_e32 v65, v6
	v_mov_b32_e32 v146, v6
	v_mov_b32_e32 v147, v6
	v_mov_b32_e32 v148, v6
	v_mov_b32_e32 v149, v6
	s_lshl_b32 s98, s76, 8
	s_ashr_i32 s99, s98, 31
	s_lshl_b64 s[98:99], s[98:99], 2
	v_readlane_b32 s100, v255, 7
	v_readlane_b32 s101, v255, 8
	s_add_u32 s98, s100, s98
	s_addc_u32 s99, s101, s99
	v_mov_b32_e32 v250, v199
	v_ashrrev_i32_e32 v251, 31, v199
	v_lshl_add_u64 v[250:251], v[250:251], 2, s[98:99]
	global_load_dword v248, v[250:251], off offset:192
	global_load_dword v249, v[250:251], off offset:704
	s_cmp_eq_u64 s[4:5], 0
	s_cbranch_scc0 .Lg3h_w47
	s_lshl_b32 s98, s76, 8
	v_or_b32_e32 v252, s98, v0
	v_ashrrev_i32_e32 v253, 31, v252
	v_lshl_add_u64 v[252:253], v[252:253], 2, s[44:45]
	global_load_dword v246, v[252:253], off
	s_branch .Lg3h_done

; template <class Epi, class Sched, bool ALIGN_EPI = false, bool SP2 = false, bool A_TILED = false, bool B_TILED = false>
; __device__ __forceinline__ void gemm_phase(PG8_LAS unsigned char* lds, const Gemm g, const Sched& S, const Epi& E) {
;     ...
;         if (!chain) {
; #pragma unroll
;         for (int a = 0; a < 2; ++a)
; #pragma unroll
;             for (int b = 0; b < 2; ++b)
; #pragma unroll
;                 for (int m = 0; m < 4; ++m)
; #pragma unroll
;                     for (int n = 0; n < 2; ++n) acc[a][b][m][n] = (f32x4){0.f, 0.f, 0.f, 0.f};
;         }
;         cur = nxt; cA = nA; cB = nB; ++ui; nt = cur.nt;
.LBB0_1068:
	s_add_u32 s65, s34, 0x100
	s_addc_u32 s66, s35, 0
	s_add_u32 s34, s36, 0xc000
	v_mov_b32_e32 v2, 0
	s_addc_u32 s35, s37, 0
	s_mov_b32 s67, -2
	v_mov_b32_e32 v3, v2
	v_mov_b32_e32 v4, v2
	v_mov_b32_e32 v5, v2
	v_mov_b32_e32 v6, v2
	v_mov_b32_e32 v7, v2
	v_mov_b32_e32 v8, v2
	v_mov_b32_e32 v9, v2
	v_mov_b32_e32 v18, v2
	v_mov_b32_e32 v19, v2
	v_mov_b32_e32 v20, v2
	v_mov_b32_e32 v21, v2
	v_mov_b32_e32 v22, v2
	v_mov_b32_e32 v23, v2
	v_mov_b32_e32 v24, v2
	v_mov_b32_e32 v25, v2
	v_mov_b32_e32 v34, v2
	v_mov_b32_e32 v35, v2
	v_mov_b32_e32 v36, v2
	v_mov_b32_e32 v37, v2
	v_mov_b32_e32 v38, v2
	v_mov_b32_e32 v39, v2
	v_mov_b32_e32 v40, v2
	v_mov_b32_e32 v41, v2
	s_nop 0
	v_mov_b32_e32 v50, v2
	v_mov_b32_e32 v51, v2
	v_mov_b32_e32 v52, v2
	v_mov_b32_e32 v53, v2
	v_mov_b32_e32 v54, v2
	v_mov_b32_e32 v55, v2
	v_mov_b32_e32 v56, v2
	v_mov_b32_e32 v57, v2
	v_mov_b32_e32 v10, v2
	v_mov_b32_e32 v11, v2
	v_mov_b32_e32 v12, v2
	v_mov_b32_e32 v13, v2
	v_mov_b32_e32 v14, v2
	v_mov_b32_e32 v15, v2
	v_mov_b32_e32 v16, v2
	v_mov_b32_e32 v17, v2
	v_mov_b32_e32 v26, v2
	v_mov_b32_e32 v27, v2
	v_mov_b32_e32 v28, v2
	v_mov_b32_e32 v29, v2
	v_mov_b32_e32 v30, v2
	v_mov_b32_e32 v31, v2
	v_mov_b32_e32 v32, v2
	v_mov_b32_e32 v33, v2
	v_mov_b32_e32 v42, v2
	v_mov_b32_e32 v43, v2
	v_mov_b32_e32 v44, v2
	v_mov_b32_e32 v45, v2
	v_mov_b32_e32 v46, v2
	v_mov_b32_e32 v47, v2
	v_mov_b32_e32 v48, v2
	v_mov_b32_e32 v49, v2
	v_mov_b32_e32 v58, v2
	v_mov_b32_e32 v59, v2
	v_mov_b32_e32 v60, v2
	v_mov_b32_e32 v61, v2
	v_mov_b32_e32 v62, v2
	v_mov_b32_e32 v63, v2
	v_mov_b32_e32 v64, v2
	v_mov_b32_e32 v65, v2
	v_mov_b32_e32 v66, v2
	v_mov_b32_e32 v67, v2
	v_mov_b32_e32 v68, v2
	v_mov_b32_e32 v69, v2
	v_mov_b32_e32 v70, v2
	v_mov_b32_e32 v71, v2
	v_mov_b32_e32 v72, v2
	v_mov_b32_e32 v73, v2
	v_mov_b32_e32 v82, v2
	v_mov_b32_e32 v83, v2
	v_mov_b32_e32 v84, v2
	v_mov_b32_e32 v85, v2
	v_mov_b32_e32 v86, v2
	v_mov_b32_e32 v87, v2
	v_mov_b32_e32 v88, v2
	v_mov_b32_e32 v89, v2
	v_mov_b32_e32 v98, v2
	v_mov_b32_e32 v99, v2
	v_mov_b32_e32 v100, v2
	v_mov_b32_e32 v101, v2
	v_mov_b32_e32 v102, v2
	v_mov_b32_e32 v103, v2
	v_mov_b32_e32 v104, v2
	v_mov_b32_e32 v105, v2
	v_mov_b32_e32 v114, v2
	v_mov_b32_e32 v115, v2
	v_mov_b32_e32 v116, v2
	v_mov_b32_e32 v117, v2
	v_mov_b32_e32 v118, v2
	v_mov_b32_e32 v119, v2
	v_mov_b32_e32 v120, v2
	v_mov_b32_e32 v121, v2
	v_mov_b32_e32 v74, v2
	v_mov_b32_e32 v75, v2
	v_mov_b32_e32 v76, v2
	v_mov_b32_e32 v77, v2
	v_mov_b32_e32 v78, v2
	v_mov_b32_e32 v79, v2
	v_mov_b32_e32 v80, v2
	v_mov_b32_e32 v81, v2
	v_mov_b32_e32 v90, v2
	v_mov_b32_e32 v91, v2
	v_mov_b32_e32 v92, v2
	v_mov_b32_e32 v93, v2
	v_mov_b32_e32 v94, v2
	v_mov_b32_e32 v95, v2
	v_mov_b32_e32 v96, v2
	v_mov_b32_e32 v97, v2
	v_mov_b32_e32 v106, v2
	v_mov_b32_e32 v107, v2
	v_mov_b32_e32 v108, v2
	v_mov_b32_e32 v109, v2
	v_mov_b32_e32 v110, v2
	v_mov_b32_e32 v111, v2
	v_mov_b32_e32 v112, v2
	v_mov_b32_e32 v113, v2
	v_mov_b32_e32 v122, v2
	v_mov_b32_e32 v123, v2
	v_mov_b32_e32 v124, v2
	v_mov_b32_e32 v125, v2
	v_mov_b32_e32 v126, v2
	v_mov_b32_e32 v127, v2
	v_mov_b32_e32 v128, v2
	v_mov_b32_e32 v129, v2
